# diff fast loop: threshold test on the lane-local score maximum (wave-uniform branch needs no cross-half combine); the permlane cross-half max moved to the rare fall-back stub
# baseline (speedup 1.0000x reference)
.Lf_462:
	s_and_b32 s17, s19, 0x18000
	v_add_u32_e32 v0, s17, v227
	v_add_u32_e32 v2, v0, v228
	ds_read_b128 v[96:99], v2
	ds_read_b128 v[100:103], v2 offset:4096
	v_add_u32_e32 v2, v0, v226
	ds_read_b128 v[180:183], v2
	ds_read_b128 v[230:233], v2 offset:4096
	v_add_u32_e32 v2, v0, v225
	v_add_u32_e32 v0, v0, v224
	s_min_u32 s16, s28, 1
	ds_read_b128 v[234:237], v2
	ds_read_b128 v[238:241], v2 offset:4096
	ds_read_b128 v[242:245], v0
	ds_read_b128 v[246:249], v0 offset:4096
	s_lshl_b32 s16, s16, 15
	s_sub_i32 s16, s19, s16
	s_and_b32 s16, s16, 0x18000
	v_add_u32_e32 v0, s16, v195
	s_setprio 1
	s_waitcnt lgkmcnt(6)
	v_mfma_f32_32x32x16_bf16 v[112:127], v[96:99], v[156:159], 0
	s_add_i32 s22, s13, 1
	s_add_i32 s61, s19, 0x8000
	s_add_i32 s20, s61, 0x10000
	s_and_b32 s20, s20, 0x18000
	v_mfma_f32_32x32x16_bf16 v[96:111], v[100:103], v[156:159], 0
	s_add_i32 s20, s20, s23
	s_add_i32 s62, s22, -2
	s_cmpk_gt_u32 s62, 0x41
	s_cselect_b32 s61, 1, 0
	s_waitcnt lgkmcnt(4)
	v_mfma_f32_32x32x16_bf16 v[112:127], v[180:183], v[152:155], v[112:127]
	s_cmp_lt_u32 s62, 62
	s_cselect_b32 s16, 0, 0xffffffc0
	s_cselect_b32 s17, s9, s10
	s_add_i32 s16, s16, s22
	v_mfma_f32_32x32x16_bf16 v[96:111], v[230:233], v[152:155], v[96:111]
	s_lshl_b32 s16, s16, 6
	s_add_i32 s62, s16, s17
	s_ashr_i32 s63, s62, 31
	s_add_u32 s30, s62, s11
	s_waitcnt lgkmcnt(2)
	v_mfma_f32_32x32x16_bf16 v[112:127], v[234:237], v[148:151], v[112:127]
	s_addc_u32 s31, s63, 0
	s_lshl_b64 s[30:31], s[30:31], 7
	s_add_u32 s34, s95, s30
	s_addc_u32 s35, s3, s31
	v_mfma_f32_32x32x16_bf16 v[96:111], v[238:241], v[148:151], v[96:111]
	s_add_u32 s16, s62, s12
	s_addc_u32 s17, s63, 0
	s_lshl_b64 s[16:17], s[16:17], 7
	s_add_u32 s16, s95, s16
	s_waitcnt lgkmcnt(0)
	v_mfma_f32_32x32x16_bf16 v[112:127], v[242:245], v[144:147], v[112:127]
	s_addc_u32 s17, s3, s17
	s_add_u32 s30, s14, s30
	s_addc_u32 s31, s15, s31
	v_mfma_f32_32x32x16_bf16 v[96:111], v[246:249], v[144:147], v[96:111]
	ds_read_b64_tr_b16 v[176:177], v0 offset:16384
	ds_read_b64_tr_b16 v[178:179], v0 offset:16896
	ds_read_b64_tr_b16 v[172:173], v0 offset:17408
	ds_read_b64_tr_b16 v[174:175], v0 offset:17920
	ds_read_b64_tr_b16 v[168:169], v0 offset:18432
	ds_read_b64_tr_b16 v[170:171], v0 offset:18944
	ds_read_b64_tr_b16 v[164:165], v0 offset:19456
	ds_read_b64_tr_b16 v[166:167], v0 offset:19968
	ds_read_b64_tr_b16 v[160:161], v0 offset:20480
	ds_read_b64_tr_b16 v[162:163], v0 offset:20992
	ds_read_b64_tr_b16 v[10:11], v0 offset:21504
	ds_read_b64_tr_b16 v[12:13], v0 offset:22016
	ds_read_b64_tr_b16 v[6:7], v0 offset:22528
	ds_read_b64_tr_b16 v[8:9], v0 offset:23040
	ds_read_b64_tr_b16 v[2:3], v0 offset:23552
	ds_read_b64_tr_b16 v[4:5], v0 offset:24064
	s_setprio 0
	v_max3_f32 v14, v112, v113, v114
	v_max3_f32 v15, v115, v116, v117
	v_max3_f32 v180, v118, v119, v120
	v_max3_f32 v181, v121, v122, v123
	v_max3_f32 v182, v124, v125, v126
	v_max3_f32 v183, v96, v97, v98
	v_max3_f32 v230, v99, v100, v101
	v_max3_f32 v231, v102, v103, v104
	s_nop 0
	v_max3_f32 v14, v14, v15, v180
	v_max3_f32 v232, v105, v106, v107
	v_max3_f32 v15, v181, v182, v127
	v_max3_f32 v233, v108, v109, v110
	v_max3_f32 v180, v183, v230, v231
	v_max3_f32 v181, v232, v233, v111
	s_nop 0
	v_max3_f32 v14, v14, v15, v180
	v_max_f32_e32 v14, v14, v181
	v_cmp_lt_f32_e32 vcc, 0x42800000, v14
	s_waitcnt lgkmcnt(0)
	s_cbranch_vccz .Lf_459
	s_branch .Lf_foldrare
.Lf_foldrare:
	v_mov_b32_e32 v15, v14
	s_nop 1
	v_permlane32_swap_b32_e32 v15, v14
	s_nop 1
	v_max_f32_e32 v14, v14, v15
	s_nop 7
	v_mov_b32_e32 v80, v84
	s_nop 0
	v_mov_b32_e32 v81, v80
	v_mov_b32_e32 v82, v80
	v_mov_b32_e32 v83, v80
	v_mov_b32_e32 v84, v80
	v_mov_b32_e32 v85, v80
	v_mov_b32_e32 v86, v80
	v_mov_b32_e32 v87, v80
	v_mov_b32_e32 v88, v80
	v_mov_b32_e32 v89, v80
	v_mov_b32_e32 v90, v80
	v_mov_b32_e32 v91, v80
	v_mov_b32_e32 v92, v80
	v_mov_b32_e32 v93, v80
	v_mov_b32_e32 v94, v80
	v_mov_b32_e32 v95, v80
	s_nop 1
	s_branch .Lf_to463
